# pair path: previous block's P V MFMAs issued between this block's QK MFMAs and its softmax VALU (matrix pipe busy under the exp / cvt / sum work)
# baseline (speedup 1.0000x reference)
; #define LAS __attribute__((address_space(3)))
; #define MFMA16(a, b, c) __builtin_amdgcn_mfma_f32_16x16x32_bf16(a, b, c, 0, 0, 0)
; #define NSA_LD1(jj) do { kr = *(const bf16x8*)((const char*)Kt + (size_t)(jj) * 8192 + kgo); vr = *(const bf16x8*)((const char*)Vt + (jj) * 128 + vgo); } while (0)
; template <int MODE> ...
;     ...
;     for (int jA = j0, pp = 0; jA <= qb; jA += 2, pp ^= 1) {
;       for (int sub = 0; sub < 2; ++sub) {
;         const int j = jA + sub; if (j > qb) break;
;         const bool pre = j + 2 <= qb;
;         if (pre) NSA_LD1(j + 2);
;         const LAS bf16_t* Ks = stage + pp * 18432 + sub * 9216; const LAS bf16_t* Vs = Ks + 4608;
;         const bool far = MODE == 0 && (qb - j >= 17);
; #pragma unroll
;         for (int tile = 0; tile < 2; ++tile) {
;             const int tl0 = wave * 8 + tile * 4, t0 = qb * 64 + tl0;
;             unsigned mb[4] = {1u, 1u, 1u, 1u};
;             if (MODE == 0) {
; #pragma unroll
;                 for (int i = 0; i < 4; ++i) mb[i] = (masks[(tl0 + i) * 4 + (j >> 5)] >> (j & 31)) & 1u; }
;             if (MODE == 1 || __builtin_amdgcn_readfirstlane((int)(mb[0] | mb[1] | mb[2] | mb[3]))) {
;                 f32x4 sc[4];
; #pragma unroll
;                 for (int cc = 0; cc < 4; ++cc) { const LAS bf16_t* kp = Ks + (cc * 16 + r16) * 72 + q4 * 8;
;                     sc[cc] = MFMA16(aq[tile][0], *(const LAS bf16x8*)kp, z4); sc[cc] = MFMA16(aq[tile][1], *(const LAS bf16x8*)(kp + 32), sc[cc]); }
.Lnsa_blk_loop:
	s_add_i32 s14, s57, 2
	s_min_u32 s15, s14, s19
	v_readlane_b32 s0, v179, s15
	v_readlane_b32 s1, v228, s15
	s_cmp_lt_u32 s15, 64
	s_cselect_b32 s95, s0, s1
	s_and_b32 s73, s95, 255
	s_and_b32 s0, s14, 3
	s_lshl_b32 s0, s0, 14
	s_add_i32 s0, s0, s33
	s_lshl_b32 s1, s73, 13
	s_add_u32 s70, s66, s1
	s_addc_u32 s71, s67, 0
	s_mov_b32 m0, s0
	s_lshl_b32 s1, s73, 7
	global_load_lds_dwordx4 v174, s[70:71]
	s_add_u32 s70, s68, s1
	s_addc_u32 s71, s69, 0
	s_add_i32 m0, s0, 8192
	s_add_i32 s1, s14, 0
	global_load_lds_dwordx4 v175, s[70:71]
	s_and_b32 s73, s93, 255
	s_bfe_u32 s34, s93, 0x20008
	s_bfe_u32 s42, s93, 0x2000a
	s_sub_i32 s47, s18, s73
	s_lshr_b32 s46, s73, 5
	s_and_b32 s72, s73, 31
	s_and_b32 s35, s57, 3
	s_lshl_b32 s35, s35, 14
	v_add_u32_e32 v170, s35, v98
	v_add_u32_e32 v171, v170, v0
	v_add_u32_e32 v172, s35, v99
	v_add_u32_e32 v173, v172, v0
	s_lshl_b32 s0, s47, 6
	v_add_u32_e32 v229, s0, v176
	s_lshl_b32 s0, s47, 8
	v_add_u32_e32 v231, s0, v177
	s_cmp_eq_u32 s46, s21
	s_cbranch_scc1 .Lnsa_mwok_9
	s_mov_b32 s21, s46
	s_cmp_lg_u32 s54, 0
	s_cbranch_scc1 .Lnsa_mwok_9
	s_lshl_b32 s15, s46, 2
	v_add_u32_e32 v230, s15, v178
	ds_read_b32 v232, v230
	ds_read_b32 v233, v230 offset:64
	s_waitcnt lgkmcnt(0)
.Lnsa_mwok_9:
	v_bfe_i32 v234, v232, s72, 1
	v_bfe_i32 v235, v233, s72, 1
	s_cmp_eq_u32 s34, 3
	s_cbranch_scc0 .Lnsa_nopair_10
	s_cmp_eq_u32 s42, 1
	s_cbranch_scc1 .Lnsa_nopair_10
	s_cmp_eq_u32 s42, 2
	s_cbranch_scc1 .Lnsa_pfar_13
	v_add_u32_e32 v230, 16, v231
	v_bfi_b32 v253, v234, v231, v226
	v_bfi_b32 v230, v235, v230, v226
	ds_read2_b32 v[66:67], v253 offset0:39 offset1:38
	ds_read2_b32 v[68:69], v253 offset0:37 offset1:36
	ds_read2_b32 v[70:71], v253 offset0:35 offset1:34
	ds_read2_b32 v[72:73], v253 offset0:33 offset1:32
	ds_read2_b32 v[74:75], v253 offset0:7 offset1:6
	ds_read2_b32 v[76:77], v253 offset0:5 offset1:4
	ds_read2_b32 v[78:79], v253 offset0:3 offset1:2
	ds_read2_b32 v[80:81], v253 offset0:1 offset1:0
	ds_read2_b32 v[236:237], v230 offset0:39 offset1:38
	ds_read2_b32 v[238:239], v230 offset0:37 offset1:36
	ds_read2_b32 v[240:241], v230 offset0:35 offset1:34
	ds_read2_b32 v[242:243], v230 offset0:33 offset1:32
	ds_read_b128 v[50:53], v170 offset:0
	ds_read_b128 v[54:57], v171 offset:0
	s_waitcnt lgkmcnt(0)
	ds_read_b128 v[58:61], v170 offset:512
	ds_read_b128 v[62:65], v171 offset:512
	ds_read2_b32 v[244:245], v230 offset0:7 offset1:6
	ds_read2_b32 v[246:247], v230 offset0:5 offset1:4
	ds_read2_b32 v[248:249], v230 offset0:3 offset1:2
	ds_read2_b32 v[250:251], v230 offset0:1 offset1:0
	v_mfma_f32_16x16x32_bf16 v[66:69], v[50:53], v[34:37], v[66:69]
	v_mfma_f32_16x16x32_bf16 v[66:69], v[54:57], v[38:41], v[66:69]
	v_mfma_f32_16x16x32_bf16 v[236:239], v[50:53], v[42:45], v[236:239]
	v_mfma_f32_16x16x32_bf16 v[236:239], v[54:57], v[46:49], v[236:239]
	ds_read_b128 v[50:53], v170 offset:4096
	ds_read_b128 v[54:57], v171 offset:4096
	s_waitcnt lgkmcnt(6)
	v_mfma_f32_16x16x32_bf16 v[70:73], v[58:61], v[34:37], v[70:73]
	v_mfma_f32_16x16x32_bf16 v[70:73], v[62:65], v[38:41], v[70:73]
	v_mfma_f32_16x16x32_bf16 v[240:243], v[58:61], v[42:45], v[240:243]
	v_mfma_f32_16x16x32_bf16 v[240:243], v[62:65], v[46:49], v[240:243]
	ds_read_b128 v[58:61], v170 offset:4608
	ds_read_b128 v[62:65], v171 offset:4608
	s_waitcnt lgkmcnt(2)
	v_mfma_f32_16x16x32_bf16 v[74:77], v[50:53], v[34:37], v[74:77]
	v_mfma_f32_16x16x32_bf16 v[74:77], v[54:57], v[38:41], v[74:77]
	v_mfma_f32_16x16x32_bf16 v[244:247], v[50:53], v[42:45], v[244:247]
	v_mfma_f32_16x16x32_bf16 v[244:247], v[54:57], v[46:49], v[244:247]
	s_waitcnt lgkmcnt(0)
	v_mfma_f32_16x16x32_bf16 v[78:81], v[58:61], v[34:37], v[78:81]
	v_mfma_f32_16x16x32_bf16 v[78:81], v[62:65], v[38:41], v[78:81]
	v_mfma_f32_16x16x32_bf16 v[248:251], v[58:61], v[42:45], v[248:251]
	v_mfma_f32_16x16x32_bf16 v[248:251], v[62:65], v[46:49], v[248:251]
	s_branch .Lnsa_psm_14

; #define LAS __attribute__((address_space(3)))
; #define CBAR() asm volatile("" ::: "memory")
; #define MFMA16(a, b, c) __builtin_amdgcn_mfma_f32_16x16x32_bf16(a, b, c, 0, 0, 0)
; template <int MODE> ...
;     ...
;                 for (int ks = 0; ks < 2; ++ks) { const bf16x8 aP = *(const LAS bf16x8*)(Pb + r16 * 72 + ks * 32 + q4 * 8);
; #pragma unroll
;                     for (int nt = 0; nt < 4; ++nt) os[tile][nt] = MFMA16(aP, *(const LAS bf16x8*)(Vs + (nt * 16 + r16) * 72 + ks * 32 + q4 * 8), os[tile][nt]); }
;                 CBAR();
.Lnsa_psm_14:
	s_waitcnt lgkmcnt(0)
	s_cmp_eq_u32 s43, 0
	s_cbranch_scc1 .Lnsa_pvnone_15
	v_add_u32_e32 v253, s75, v99
	v_add_u32_e32 v230, v253, v0
	ds_read_b128 v[50:53], v253 offset:0
	ds_read_b128 v[54:57], v230 offset:0
	ds_read_b128 v[58:61], v253 offset:2048
	ds_read_b128 v[62:65], v230 offset:2048
	s_cmp_eq_u32 s43, 3
	s_cbranch_scc0 .Lnsa_pvone_16
	s_waitcnt lgkmcnt(2)
	v_mfma_f32_16x16x32_bf16 v[2:5], v[50:53], v[82:85], v[2:5]
	v_mfma_f32_16x16x32_bf16 v[2:5], v[54:57], v[86:89], v[2:5]
	v_mfma_f32_16x16x32_bf16 v[18:21], v[50:53], v[90:93], v[18:21]
	v_mfma_f32_16x16x32_bf16 v[18:21], v[54:57], v[94:97], v[18:21]
	ds_read_b128 v[50:53], v253 offset:4096
	ds_read_b128 v[54:57], v230 offset:4096
	s_waitcnt lgkmcnt(2)
	v_mfma_f32_16x16x32_bf16 v[6:9], v[58:61], v[82:85], v[6:9]
	v_mfma_f32_16x16x32_bf16 v[6:9], v[62:65], v[86:89], v[6:9]
	v_mfma_f32_16x16x32_bf16 v[22:25], v[58:61], v[90:93], v[22:25]
	v_mfma_f32_16x16x32_bf16 v[22:25], v[62:65], v[94:97], v[22:25]
	ds_read_b128 v[58:61], v253 offset:6144
	ds_read_b128 v[62:65], v230 offset:6144
	s_waitcnt lgkmcnt(2)
	v_mfma_f32_16x16x32_bf16 v[10:13], v[50:53], v[82:85], v[10:13]
	v_mfma_f32_16x16x32_bf16 v[10:13], v[54:57], v[86:89], v[10:13]
	v_mfma_f32_16x16x32_bf16 v[26:29], v[50:53], v[90:93], v[26:29]
	v_mfma_f32_16x16x32_bf16 v[26:29], v[54:57], v[94:97], v[26:29]
	s_waitcnt lgkmcnt(0)
	v_mfma_f32_16x16x32_bf16 v[14:17], v[58:61], v[82:85], v[14:17]
	v_mfma_f32_16x16x32_bf16 v[14:17], v[62:65], v[86:89], v[14:17]
	v_mfma_f32_16x16x32_bf16 v[30:33], v[58:61], v[90:93], v[30:33]
	v_mfma_f32_16x16x32_bf16 v[30:33], v[62:65], v[94:97], v[30:33]
	s_branch .Lnsa_pvend_18
.Lnsa_pvone_16:
	s_cmp_eq_u32 s43, 2
	s_cbranch_scc1 .Lnsa_pvt1_17
	s_waitcnt lgkmcnt(2)
	v_mfma_f32_16x16x32_bf16 v[2:5], v[50:53], v[82:85], v[2:5]
	v_mfma_f32_16x16x32_bf16 v[2:5], v[54:57], v[86:89], v[2:5]
	ds_read_b128 v[50:53], v253 offset:4096
	ds_read_b128 v[54:57], v230 offset:4096
	s_waitcnt lgkmcnt(2)
	v_mfma_f32_16x16x32_bf16 v[6:9], v[58:61], v[82:85], v[6:9]
	v_mfma_f32_16x16x32_bf16 v[6:9], v[62:65], v[86:89], v[6:9]
	ds_read_b128 v[58:61], v253 offset:6144
	ds_read_b128 v[62:65], v230 offset:6144
	s_waitcnt lgkmcnt(2)
	v_mfma_f32_16x16x32_bf16 v[10:13], v[50:53], v[82:85], v[10:13]
	v_mfma_f32_16x16x32_bf16 v[10:13], v[54:57], v[86:89], v[10:13]
	s_waitcnt lgkmcnt(0)
	v_mfma_f32_16x16x32_bf16 v[14:17], v[58:61], v[82:85], v[14:17]
	v_mfma_f32_16x16x32_bf16 v[14:17], v[62:65], v[86:89], v[14:17]
	s_branch .Lnsa_pvend_18
.Lnsa_pvt1_17:
	s_waitcnt lgkmcnt(2)
	v_mfma_f32_16x16x32_bf16 v[18:21], v[50:53], v[90:93], v[18:21]
	v_mfma_f32_16x16x32_bf16 v[18:21], v[54:57], v[94:97], v[18:21]
	ds_read_b128 v[50:53], v253 offset:4096
	ds_read_b128 v[54:57], v230 offset:4096
	s_waitcnt lgkmcnt(2)
	v_mfma_f32_16x16x32_bf16 v[22:25], v[58:61], v[90:93], v[22:25]
	v_mfma_f32_16x16x32_bf16 v[22:25], v[62:65], v[94:97], v[22:25]
	ds_read_b128 v[58:61], v253 offset:6144
	ds_read_b128 v[62:65], v230 offset:6144
	s_waitcnt lgkmcnt(2)
	v_mfma_f32_16x16x32_bf16 v[26:29], v[50:53], v[90:93], v[26:29]
	v_mfma_f32_16x16x32_bf16 v[26:29], v[54:57], v[94:97], v[26:29]
	s_waitcnt lgkmcnt(0)
	v_mfma_f32_16x16x32_bf16 v[30:33], v[58:61], v[90:93], v[30:33]
	v_mfma_f32_16x16x32_bf16 v[30:33], v[62:65], v[94:97], v[30:33]

; #define LAS __attribute__((address_space(3)))
; #define CBAR() asm volatile("" ::: "memory")
; #define MFMA16(a, b, c) __builtin_amdgcn_mfma_f32_16x16x32_bf16(a, b, c, 0, 0, 0)
; __device__ __forceinline__ bf16_t tobf(float x) { return (bf16_t)pk2(x, 0.f); }
; __device__ __forceinline__ float ex2(float x) { return __builtin_amdgcn_exp2f(x); }
; template <int MODE> ...
;     ...
;                 if (far) {
; #pragma unroll
;                     for (int cc = 0; cc < 4; ++cc)
; #pragma unroll
;                         for (int i = 0; i < 4; ++i) { const float p = mb[i] ? ex2(sc[cc][i] + bfar) : 0.f; ls[tile][i] += p; Pb[(4 * q4 + i) * 72 + cc * 16 + r16] = tobf(p); }
;                 } else {
; #pragma unroll
;                     for (int cc = 0; cc < 4; ++cc) { const int pos = j * 64 + cc * 16 + r16;
; #pragma unroll
;                         for (int i = 0; i < 4; ++i) { const int dist = t0 + i - pos; const bool ok = MODE ? ((unsigned)dist < 512u) : (dist >= 0 && mb[i]);
;                             const float p = ok ? ex2(sc[cc][i] + bt[clampd(dist)]) : 0.f; ls[tile][i] += p; Pb[(4 * q4 + i) * 72 + cc * 16 + r16] = tobf(p); } }
;                 }
;                 CBAR();
; #pragma unroll
;                 for (int ks = 0; ks < 2; ++ks) { const bf16x8 aP = *(const LAS bf16x8*)(Pb + r16 * 72 + ks * 32 + q4 * 8);
; #pragma unroll
;                     for (int nt = 0; nt < 4; ++nt) os[tile][nt] = MFMA16(aP, *(const LAS bf16x8*)(Vs + (nt * 16 + r16) * 72 + ks * 32 + q4 * 8), os[tile][nt]); }
;                 CBAR();
.Lnsa_pvnone_15:
	v_exp_f32_e32 v66, v66
	v_exp_f32_e32 v67, v67
	v_exp_f32_e32 v68, v68
	v_exp_f32_e32 v69, v69
	v_exp_f32_e32 v70, v70
	v_exp_f32_e32 v71, v71
	v_exp_f32_e32 v72, v72
	v_exp_f32_e32 v73, v73
	v_exp_f32_e32 v74, v74
	v_exp_f32_e32 v75, v75
	v_exp_f32_e32 v76, v76
	v_exp_f32_e32 v77, v77
	v_exp_f32_e32 v78, v78
	v_exp_f32_e32 v79, v79
	v_exp_f32_e32 v80, v80
	v_exp_f32_e32 v81, v81
	v_exp_f32_e32 v236, v236
	v_exp_f32_e32 v237, v237
	v_exp_f32_e32 v238, v238
	v_exp_f32_e32 v239, v239
	v_exp_f32_e32 v240, v240
	v_exp_f32_e32 v241, v241
	v_exp_f32_e32 v242, v242
	v_exp_f32_e32 v243, v243
	v_exp_f32_e32 v244, v244
	v_exp_f32_e32 v245, v245
	v_exp_f32_e32 v246, v246
	v_exp_f32_e32 v247, v247
	v_exp_f32_e32 v248, v248
	v_exp_f32_e32 v249, v249
	v_exp_f32_e32 v250, v250
	v_exp_f32_e32 v251, v251
	v_cvt_pk_bf16_f32 v82, v66, v67
	v_cvt_pk_bf16_f32 v83, v68, v69
	v_cvt_pk_bf16_f32 v84, v70, v71
	v_cvt_pk_bf16_f32 v85, v72, v73
	v_cvt_pk_bf16_f32 v86, v74, v75
	v_cvt_pk_bf16_f32 v87, v76, v77
	v_cvt_pk_bf16_f32 v88, v78, v79
	v_cvt_pk_bf16_f32 v89, v80, v81
	v_add_f32_e32 v66, v66, v67
	v_add_f32_e32 v68, v68, v69
	v_add_f32_e32 v70, v70, v71
	v_add_f32_e32 v72, v72, v73
	v_add_f32_e32 v74, v74, v75
	v_add_f32_e32 v76, v76, v77
	v_add_f32_e32 v78, v78, v79
	v_add_f32_e32 v80, v80, v81
	v_add_f32_e32 v66, v66, v68
	v_add_f32_e32 v70, v70, v72
	v_add_f32_e32 v74, v74, v76
	v_add_f32_e32 v78, v78, v80
	v_add_f32_e32 v66, v66, v70
	v_add_f32_e32 v74, v74, v78
	v_add_f32_e32 v66, v66, v74
	v_add_f32_e32 v215, v215, v66
	v_cvt_pk_bf16_f32 v90, v236, v237
	v_cvt_pk_bf16_f32 v91, v238, v239
	v_cvt_pk_bf16_f32 v92, v240, v241
	v_cvt_pk_bf16_f32 v93, v242, v243
	v_cvt_pk_bf16_f32 v94, v244, v245
	v_cvt_pk_bf16_f32 v95, v246, v247
	v_cvt_pk_bf16_f32 v96, v248, v249
	v_cvt_pk_bf16_f32 v97, v250, v251
	v_add_f32_e32 v236, v236, v237
	v_add_f32_e32 v238, v238, v239
	v_add_f32_e32 v240, v240, v241
	v_add_f32_e32 v242, v242, v243
	v_add_f32_e32 v244, v244, v245
	v_add_f32_e32 v246, v246, v247
	v_add_f32_e32 v248, v248, v249
	v_add_f32_e32 v250, v250, v251
	v_add_f32_e32 v236, v236, v238
	v_add_f32_e32 v240, v240, v242
	v_add_f32_e32 v244, v244, v246
	v_add_f32_e32 v248, v248, v250
	v_add_f32_e32 v236, v236, v240
	v_add_f32_e32 v244, v244, v248
	v_add_f32_e32 v236, v236, v244
	v_add_f32_e32 v224, v224, v236
	s_branch .Lnsa_blkend_12
.Lnsa_nopair_10:
	s_cmp_eq_u32 s43, 0
	s_cbranch_scc1 .Lnsa_pvnone_19
	v_add_u32_e32 v253, s75, v99
	v_add_u32_e32 v230, v253, v0
	ds_read_b128 v[50:53], v253 offset:0
	ds_read_b128 v[54:57], v230 offset:0
	ds_read_b128 v[58:61], v253 offset:2048
	ds_read_b128 v[62:65], v230 offset:2048
	s_cmp_eq_u32 s43, 3
	s_cbranch_scc0 .Lnsa_pvone_20
	s_waitcnt lgkmcnt(2)
	v_mfma_f32_16x16x32_bf16 v[2:5], v[50:53], v[82:85], v[2:5]
	v_mfma_f32_16x16x32_bf16 v[2:5], v[54:57], v[86:89], v[2:5]
	v_mfma_f32_16x16x32_bf16 v[18:21], v[50:53], v[90:93], v[18:21]
	v_mfma_f32_16x16x32_bf16 v[18:21], v[54:57], v[94:97], v[18:21]
	ds_read_b128 v[50:53], v253 offset:4096
	ds_read_b128 v[54:57], v230 offset:4096
	s_waitcnt lgkmcnt(2)
	v_mfma_f32_16x16x32_bf16 v[6:9], v[58:61], v[82:85], v[6:9]
	v_mfma_f32_16x16x32_bf16 v[6:9], v[62:65], v[86:89], v[6:9]
	v_mfma_f32_16x16x32_bf16 v[22:25], v[58:61], v[90:93], v[22:25]
	v_mfma_f32_16x16x32_bf16 v[22:25], v[62:65], v[94:97], v[22:25]
	ds_read_b128 v[58:61], v253 offset:6144
	ds_read_b128 v[62:65], v230 offset:6144
	s_waitcnt lgkmcnt(2)
	v_mfma_f32_16x16x32_bf16 v[10:13], v[50:53], v[82:85], v[10:13]
	v_mfma_f32_16x16x32_bf16 v[10:13], v[54:57], v[86:89], v[10:13]
	v_mfma_f32_16x16x32_bf16 v[26:29], v[50:53], v[90:93], v[26:29]
	v_mfma_f32_16x16x32_bf16 v[26:29], v[54:57], v[94:97], v[26:29]
	s_waitcnt lgkmcnt(0)
	v_mfma_f32_16x16x32_bf16 v[14:17], v[58:61], v[82:85], v[14:17]
	v_mfma_f32_16x16x32_bf16 v[14:17], v[62:65], v[86:89], v[14:17]
	v_mfma_f32_16x16x32_bf16 v[30:33], v[58:61], v[90:93], v[30:33]
	v_mfma_f32_16x16x32_bf16 v[30:33], v[62:65], v[94:97], v[30:33]
	s_branch .Lnsa_pvend_22

; #define LAS __attribute__((address_space(3)))
; #define MFMA16(a, b, c) __builtin_amdgcn_mfma_f32_16x16x32_bf16(a, b, c, 0, 0, 0)
; template <int MODE> ...
;     ...
;         for (int tile = 0; tile < 2; ++tile) {
;             const int tl0 = wave * 8 + tile * 4, t0 = qb * 64 + tl0;
;             unsigned mb[4] = {1u, 1u, 1u, 1u};
;             if (MODE == 0) {
; #pragma unroll
;                 for (int i = 0; i < 4; ++i) mb[i] = (masks[(tl0 + i) * 4 + (j >> 5)] >> (j & 31)) & 1u; }
;             if (MODE == 1 || __builtin_amdgcn_readfirstlane((int)(mb[0] | mb[1] | mb[2] | mb[3]))) {
;                 f32x4 sc[4];
; #pragma unroll
;                 for (int cc = 0; cc < 4; ++cc) { const LAS bf16_t* kp = Ks + (cc * 16 + r16) * 72 + q4 * 8;
;                     sc[cc] = MFMA16(aq[tile][0], *(const LAS bf16x8*)kp, z4); sc[cc] = MFMA16(aq[tile][1], *(const LAS bf16x8*)(kp + 32), sc[cc]); }
.Lnsa_pvend_22:
	s_waitcnt lgkmcnt(0)
.Lnsa_pvnone_19:
	s_bitcmp1_b32 s34, 0
	s_cbranch_scc0 .Lnsa_single1_11
	s_cmp_eq_u32 s42, 1
	s_cbranch_scc1 .Lnsa_gen_23
	s_cmp_eq_u32 s42, 2
	s_cbranch_scc1 .Lnsa_far_24
	v_bfi_b32 v230, v234, v231, v226
	ds_read2_b32 v[66:67], v230 offset0:39 offset1:38
	ds_read2_b32 v[68:69], v230 offset0:37 offset1:36
	ds_read2_b32 v[70:71], v230 offset0:35 offset1:34
	ds_read2_b32 v[72:73], v230 offset0:33 offset1:32
	ds_read2_b32 v[74:75], v230 offset0:7 offset1:6
	ds_read2_b32 v[76:77], v230 offset0:5 offset1:4
	ds_read2_b32 v[78:79], v230 offset0:3 offset1:2
	ds_read2_b32 v[80:81], v230 offset0:1 offset1:0
	ds_read_b128 v[50:53], v170 offset:0
	ds_read_b128 v[54:57], v171 offset:0
	ds_read_b128 v[58:61], v170 offset:512
	ds_read_b128 v[62:65], v171 offset:512
	s_waitcnt lgkmcnt(2)
	v_mfma_f32_16x16x32_bf16 v[66:69], v[50:53], v[34:37], v[66:69]
	v_mfma_f32_16x16x32_bf16 v[66:69], v[54:57], v[38:41], v[66:69]
	ds_read_b128 v[50:53], v170 offset:4096
	ds_read_b128 v[54:57], v171 offset:4096
	s_waitcnt lgkmcnt(2)
	v_mfma_f32_16x16x32_bf16 v[70:73], v[58:61], v[34:37], v[70:73]
	v_mfma_f32_16x16x32_bf16 v[70:73], v[62:65], v[38:41], v[70:73]
	ds_read_b128 v[58:61], v170 offset:4608
	ds_read_b128 v[62:65], v171 offset:4608
	s_waitcnt lgkmcnt(2)
	v_mfma_f32_16x16x32_bf16 v[74:77], v[50:53], v[34:37], v[74:77]
	v_mfma_f32_16x16x32_bf16 v[74:77], v[54:57], v[38:41], v[74:77]
	s_waitcnt lgkmcnt(0)
	v_mfma_f32_16x16x32_bf16 v[78:81], v[58:61], v[34:37], v[78:81]
	v_mfma_f32_16x16x32_bf16 v[78:81], v[62:65], v[38:41], v[78:81]
	s_branch .Lnsa_ssm_25

; #define CBAR() asm volatile("" ::: "memory")
; #define NSA_ST1(st_, half_) do { LAS bf16_t* nx_ = stage + (st_) * 18432 + (half_) * 9216 + soff; *(LAS bf16x8*)nx_ = kr; *(LAS bf16x8*)(nx_ + 4608) = vr; } while (0)
; template <int MODE> ...
;     ...
;                 CBAR();
;             }
;         }
;         if (pre) NSA_ST1(pp ^ 1, sub);
;       }
;         __syncthreads();
;     }
.Lnsa_blkend_12:
	s_mov_b32 s43, s34
	s_mov_b32 s75, s35
	s_waitcnt vmcnt(2) lgkmcnt(0)
	s_barrier
	s_mov_b32 s93, s94
	s_mov_b32 s94, s95
	s_add_i32 s57, s57, 1
	s_cmp_lt_u32 s57, s92
	s_cbranch_scc1 .Lnsa_blk_loop
	s_cmp_eq_u32 s43, 0
	s_cbranch_scc1 .Lnsa_pvnone_29
	v_add_u32_e32 v253, s75, v99
	v_add_u32_e32 v230, v253, v0
	ds_read_b128 v[50:53], v253 offset:0
	ds_read_b128 v[54:57], v230 offset:0
	ds_read_b128 v[58:61], v253 offset:2048
	ds_read_b128 v[62:65], v230 offset:2048
	s_cmp_eq_u32 s43, 3
	s_cbranch_scc0 .Lnsa_pvone_30
	s_waitcnt lgkmcnt(2)
	v_mfma_f32_16x16x32_bf16 v[2:5], v[50:53], v[82:85], v[2:5]
	v_mfma_f32_16x16x32_bf16 v[2:5], v[54:57], v[86:89], v[2:5]
	v_mfma_f32_16x16x32_bf16 v[18:21], v[50:53], v[90:93], v[18:21]
	v_mfma_f32_16x16x32_bf16 v[18:21], v[54:57], v[94:97], v[18:21]
	ds_read_b128 v[50:53], v253 offset:4096
	ds_read_b128 v[54:57], v230 offset:4096
	s_waitcnt lgkmcnt(2)
	v_mfma_f32_16x16x32_bf16 v[6:9], v[58:61], v[82:85], v[6:9]
	v_mfma_f32_16x16x32_bf16 v[6:9], v[62:65], v[86:89], v[6:9]
	v_mfma_f32_16x16x32_bf16 v[22:25], v[58:61], v[90:93], v[22:25]
	v_mfma_f32_16x16x32_bf16 v[22:25], v[62:65], v[94:97], v[22:25]
	ds_read_b128 v[58:61], v253 offset:6144
	ds_read_b128 v[62:65], v230 offset:6144
	s_waitcnt lgkmcnt(2)
	v_mfma_f32_16x16x32_bf16 v[10:13], v[50:53], v[82:85], v[10:13]
	v_mfma_f32_16x16x32_bf16 v[10:13], v[54:57], v[86:89], v[10:13]
	v_mfma_f32_16x16x32_bf16 v[26:29], v[50:53], v[90:93], v[26:29]
	v_mfma_f32_16x16x32_bf16 v[26:29], v[54:57], v[94:97], v[26:29]
	s_waitcnt lgkmcnt(0)
	v_mfma_f32_16x16x32_bf16 v[14:17], v[58:61], v[82:85], v[14:17]
	v_mfma_f32_16x16x32_bf16 v[14:17], v[62:65], v[86:89], v[14:17]
	v_mfma_f32_16x16x32_bf16 v[30:33], v[58:61], v[90:93], v[30:33]
	v_mfma_f32_16x16x32_bf16 v[30:33], v[62:65], v[94:97], v[30:33]
	s_branch .Lnsa_pvend_32
